# baseline (speedup 1.0000x reference)
; __device__ __forceinline__ unsigned cvt_pk_bf16(float lo, float hi) { unsigned r; asm volatile("v_cvt_pk_bf16_f32 %0, %1, %2" : "=v"(r) : "v"(lo), "v"(hi)); return r; }
; __device__ __forceinline__ float silu_mul(float g, float u) { return g * u * __builtin_amdgcn_rcpf(1.f + __builtin_amdgcn_exp2f(-1.4426950408889634f * g)); }
;     __device__ __forceinline__ void operator()(const f32x4 (&acc)[2][2][4][2], const Unit& u, int wr, int wc, int fr, int fq) const {
;         const int row0 = u.pm * BM + wr * 64 + fr, col0 = u.pn * HALF + wc * 32 + 8 * fq;
; #pragma unroll
;         for (int ai = 0; ai < 2; ++ai)
; #pragma unroll
;             for (int m = 0; m < 4; ++m) { bf16_t* rowp = O + (size_t)(row0 + ai * HALF + m * 16) * ldc + col0;
;                 const f32x4 g0 = acc[ai][0][m][0], g1 = acc[ai][0][m][1], u0 = acc[ai][1][m][0], u1 = acc[ai][1][m][1];
;                 u32x4 w; w.x = cvt_pk_bf16(silu_mul(g0[0], u0[0]), silu_mul(g0[1], u0[1])); w.y = cvt_pk_bf16(silu_mul(g0[2], u0[2]), silu_mul(g0[3], u0[3]));
;                 w.z = cvt_pk_bf16(silu_mul(g1[0], u1[0]), silu_mul(g1[1], u1[1])); w.w = cvt_pk_bf16(silu_mul(g1[2], u1[2]), silu_mul(g1[3], u1[3]));
;                 *(u32x4*)rowp = w; }
.LBB0_73:
	v_mul_f32_e32 v157, 0xbfb8aa3b, v126
	v_mul_f32_e32 v160, 0xbfb8aa3b, v127
	v_exp_f32_e32 v157, v157
	v_exp_f32_e32 v160, v160
	v_mul_f32_e32 v122, v122, v126
	v_mul_f32_e32 v126, 0xbfb8aa3b, v128
	v_add_f32_e32 v157, 1.0, v157
	v_add_f32_e32 v160, 1.0, v160
	v_rcp_f32_e32 v157, v157
	v_rcp_f32_e32 v160, v160
	v_mul_f32_e32 v123, v123, v127
	v_exp_f32_e32 v126, v126
	v_mul_f32_e32 v127, 0xbfb8aa3b, v129
	v_exp_f32_e32 v127, v127
	v_mul_f32_e32 v122, v122, v157
	v_mul_f32_e32 v123, v123, v160
	v_cvt_pk_bf16_f32 v122, v122, v123
	v_add_f32_e32 v123, 1.0, v126
	v_rcp_f32_e32 v123, v123
	v_add_f32_e32 v126, 1.0, v127
	v_rcp_f32_e32 v126, v126
	v_mul_f32_e32 v124, v124, v128
	v_mul_f32_e32 v123, v124, v123
	v_mul_f32_e32 v124, v125, v129
	v_mul_f32_e32 v125, 0xbfb8aa3b, v118
	v_mul_f32_e32 v124, v124, v126
	v_exp_f32_e32 v125, v125
	v_mul_f32_e32 v126, 0xbfb8aa3b, v119
	v_exp_f32_e32 v126, v126
	v_cvt_pk_bf16_f32 v123, v123, v124
	v_add_f32_e32 v124, 1.0, v125
	v_rcp_f32_e32 v124, v124
	v_add_f32_e32 v125, 1.0, v126
	v_mul_f32_e32 v114, v114, v118
	v_mul_f32_e32 v118, 0xbfb8aa3b, v120
	v_rcp_f32_e32 v125, v125
	v_mul_f32_e32 v115, v115, v119
	v_exp_f32_e32 v118, v118
	v_mul_f32_e32 v119, 0xbfb8aa3b, v121
	v_exp_f32_e32 v119, v119
	v_mul_f32_e32 v114, v114, v124
	v_mul_f32_e32 v115, v115, v125
	v_cvt_pk_bf16_f32 v124, v114, v115
	v_add_f32_e32 v114, 1.0, v118
	v_rcp_f32_e32 v114, v114
	v_add_f32_e32 v115, 1.0, v119
	v_rcp_f32_e32 v115, v115
	v_mul_f32_e32 v116, v116, v120
	v_mul_f32_e32 v114, v116, v114
	v_mul_f32_e32 v116, v117, v121
	v_mul_f32_e32 v115, v116, v115
	v_mul_f32_e32 v116, 0xbfb8aa3b, v110
	v_mul_f32_e32 v117, 0xbfb8aa3b, v111
	v_exp_f32_e32 v116, v116
	v_exp_f32_e32 v117, v117
	v_mul_f32_e32 v106, v106, v110
	v_mul_f32_e32 v110, 0xbfb8aa3b, v112
	v_add_f32_e32 v116, 1.0, v116
	v_add_f32_e32 v117, 1.0, v117
	v_rcp_f32_e32 v116, v116
	v_rcp_f32_e32 v117, v117
	v_mbcnt_lo_u32_b32 v168, -1, 0
	v_mbcnt_hi_u32_b32 v168, -1, v168
	v_lshrrev_b32_e32 v169, 2, v168
	v_and_b32_e32 v170, 3, v168
	v_and_b32_e32 v171, -16, v1
	v_or_b32_e32 v171, v171, v169
	v_and_b32_e32 v172, 0xffffffe7, v152
	v_lshl_or_b32 v172, v170, 3, v172
	v_lshl_or_b32 v173, v170, 4, v169
	v_lshlrev_b32_e32 v173, 2, v173
	v_lshl_or_b32 v148, s64, 7, v172
	v_mul_f32_e32 v107, v107, v111
	v_exp_f32_e32 v110, v110
	v_mul_f32_e32 v111, 0xbfb8aa3b, v113
	v_lshl_add_u32 v156, s46, 8, v171
	v_ashrrev_i32_e32 v149, 31, v148
	v_mov_b64_e32 v[150:151], s[16:17]
	v_exp_f32_e32 v111, v111
	v_mad_i64_i32 v[158:159], s[48:49], v156, s63, v[150:151]
	v_lshlrev_b64 v[148:149], 1, v[148:149]
	v_lshl_add_u64 v[158:159], v[158:159], 0, v[148:149]
	v_mul_f32_e32 v106, v106, v116
	v_mul_f32_e32 v107, v107, v117
	v_cvt_pk_bf16_f32 v125, v114, v115
	ds_bpermute_b32 v122, v173, v122
	ds_bpermute_b32 v123, v173, v123
	ds_bpermute_b32 v124, v173, v124
	ds_bpermute_b32 v125, v173, v125
	s_waitcnt lgkmcnt(0)
	global_store_dwordx4 v[158:159], v[122:125], off
	v_cvt_pk_bf16_f32 v106, v106, v107
	v_add_f32_e32 v107, 1.0, v110
	v_rcp_f32_e32 v107, v107
	v_add_f32_e32 v110, 1.0, v111
	v_rcp_f32_e32 v110, v110
	v_mul_f32_e32 v108, v108, v112
	v_mul_f32_e32 v107, v108, v107
	v_mul_f32_e32 v108, v109, v113
	v_mul_f32_e32 v109, 0xbfb8aa3b, v102
	v_mul_f32_e32 v108, v108, v110
	v_exp_f32_e32 v109, v109
	v_mul_f32_e32 v110, 0xbfb8aa3b, v103
	v_exp_f32_e32 v110, v110
	v_cvt_pk_bf16_f32 v107, v107, v108
	v_add_f32_e32 v108, 1.0, v109
	v_rcp_f32_e32 v108, v108
	v_add_f32_e32 v109, 1.0, v110
	v_mul_f32_e32 v98, v98, v102
	v_mul_f32_e32 v102, 0xbfb8aa3b, v104
	v_rcp_f32_e32 v109, v109
	v_mul_f32_e32 v99, v99, v103
	v_exp_f32_e32 v102, v102
	v_mul_f32_e32 v103, 0xbfb8aa3b, v105
	v_exp_f32_e32 v103, v103
	v_mul_f32_e32 v98, v98, v108
	v_mul_f32_e32 v99, v99, v109
	v_cvt_pk_bf16_f32 v108, v98, v99
	v_add_f32_e32 v98, 1.0, v102
	v_rcp_f32_e32 v98, v98
	v_add_f32_e32 v99, 1.0, v103
	v_rcp_f32_e32 v99, v99
	v_mul_f32_e32 v100, v100, v104
	v_mul_f32_e32 v98, v100, v98
	v_mul_f32_e32 v100, v101, v105
	v_mul_f32_e32 v99, v100, v99
	v_mul_f32_e32 v100, 0xbfb8aa3b, v94
	v_mul_f32_e32 v101, 0xbfb8aa3b, v95
	v_exp_f32_e32 v100, v100
	v_exp_f32_e32 v101, v101
	v_mul_f32_e32 v90, v90, v94
	v_mul_f32_e32 v94, 0xbfb8aa3b, v96
	v_add_f32_e32 v100, 1.0, v100
	v_add_f32_e32 v101, 1.0, v101
	v_rcp_f32_e32 v100, v100
	v_rcp_f32_e32 v101, v101
	v_mul_f32_e32 v91, v91, v95
	v_exp_f32_e32 v94, v94
	v_mul_f32_e32 v95, 0xbfb8aa3b, v97
	v_or_b32_e32 v114, 16, v156
	v_exp_f32_e32 v95, v95
	v_mad_i64_i32 v[114:115], s[48:49], v114, s63, v[150:151]
	v_lshl_add_u64 v[114:115], v[114:115], 0, v[148:149]
	v_mul_f32_e32 v90, v90, v100
	v_mul_f32_e32 v91, v91, v101
	v_cvt_pk_bf16_f32 v109, v98, v99
	ds_bpermute_b32 v106, v173, v106
	ds_bpermute_b32 v107, v173, v107
	ds_bpermute_b32 v108, v173, v108
	ds_bpermute_b32 v109, v173, v109
	s_waitcnt lgkmcnt(0)
; __device__ __forceinline__ unsigned cvt_pk_bf16(float lo, float hi) { unsigned r; asm volatile("v_cvt_pk_bf16_f32 %0, %1, %2" : "=v"(r) : "v"(lo), "v"(hi)); return r; }
; __device__ __forceinline__ float silu_mul(float g, float u) { return g * u * __builtin_amdgcn_rcpf(1.f + __builtin_amdgcn_exp2f(-1.4426950408889634f * g)); }
;     __device__ __forceinline__ void operator()(const f32x4 (&acc)[2][2][4][2], const Unit& u, int wr, int wc, int fr, int fq) const {
;         const int row0 = u.pm * BM + wr * 64 + fr, col0 = u.pn * HALF + wc * 32 + 8 * fq;
; #pragma unroll
;         for (int ai = 0; ai < 2; ++ai)
; #pragma unroll
;             for (int m = 0; m < 4; ++m) { bf16_t* rowp = O + (size_t)(row0 + ai * HALF + m * 16) * ldc + col0;
;                 const f32x4 g0 = acc[ai][0][m][0], g1 = acc[ai][0][m][1], u0 = acc[ai][1][m][0], u1 = acc[ai][1][m][1];
;                 u32x4 w; w.x = cvt_pk_bf16(silu_mul(g0[0], u0[0]), silu_mul(g0[1], u0[1])); w.y = cvt_pk_bf16(silu_mul(g0[2], u0[2]), silu_mul(g0[3], u0[3]));
;                 w.z = cvt_pk_bf16(silu_mul(g1[0], u1[0]), silu_mul(g1[1], u1[1])); w.w = cvt_pk_bf16(silu_mul(g1[2], u1[2]), silu_mul(g1[3], u1[3]));
;                 *(u32x4*)rowp = w; }
	global_store_dwordx4 v[114:115], v[106:109], off
	v_cvt_pk_bf16_f32 v90, v90, v91
	v_add_f32_e32 v91, 1.0, v94
	v_rcp_f32_e32 v91, v91
	v_add_f32_e32 v94, 1.0, v95
	v_rcp_f32_e32 v94, v94
	v_mul_f32_e32 v92, v92, v96
	v_mul_f32_e32 v91, v92, v91
	v_mul_f32_e32 v92, v93, v97
	v_mul_f32_e32 v93, 0xbfb8aa3b, v86
	v_mul_f32_e32 v92, v92, v94
	v_exp_f32_e32 v93, v93
	v_mul_f32_e32 v94, 0xbfb8aa3b, v87
	v_exp_f32_e32 v94, v94
	v_cvt_pk_bf16_f32 v91, v91, v92
	v_add_f32_e32 v92, 1.0, v93
	v_rcp_f32_e32 v92, v92
	v_add_f32_e32 v93, 1.0, v94
	v_mul_f32_e32 v82, v82, v86
	v_mul_f32_e32 v86, 0xbfb8aa3b, v88
	v_rcp_f32_e32 v93, v93
	v_mul_f32_e32 v83, v83, v87
	v_exp_f32_e32 v86, v86
	v_mul_f32_e32 v87, 0xbfb8aa3b, v89
	v_exp_f32_e32 v87, v87
	v_mul_f32_e32 v82, v82, v92
	v_mul_f32_e32 v83, v83, v93
	v_cvt_pk_bf16_f32 v92, v82, v83
	v_add_f32_e32 v82, 1.0, v86
	v_rcp_f32_e32 v82, v82
	v_add_f32_e32 v83, 1.0, v87
	v_rcp_f32_e32 v83, v83
	v_mul_f32_e32 v84, v84, v88
	v_mul_f32_e32 v82, v84, v82
	v_mul_f32_e32 v84, v85, v89
	v_mul_f32_e32 v83, v84, v83
	v_mul_f32_e32 v84, 0xbfb8aa3b, v78
	v_mul_f32_e32 v85, 0xbfb8aa3b, v79
	v_exp_f32_e32 v84, v84
	v_exp_f32_e32 v85, v85
	v_mul_f32_e32 v74, v74, v78
	v_mul_f32_e32 v78, 0xbfb8aa3b, v80
	v_add_f32_e32 v84, 1.0, v84
	v_add_f32_e32 v85, 1.0, v85
	v_rcp_f32_e32 v84, v84
	v_rcp_f32_e32 v85, v85
	v_mul_f32_e32 v75, v75, v79
	v_exp_f32_e32 v78, v78
	v_mul_f32_e32 v79, 0xbfb8aa3b, v81
	v_or_b32_e32 v98, 32, v156
	v_exp_f32_e32 v79, v79
	v_mad_i64_i32 v[98:99], s[48:49], v98, s63, v[150:151]
	v_lshl_add_u64 v[98:99], v[98:99], 0, v[148:149]
	v_mul_f32_e32 v74, v74, v84
	v_mul_f32_e32 v75, v75, v85
	v_cvt_pk_bf16_f32 v93, v82, v83
	ds_bpermute_b32 v90, v173, v90
	ds_bpermute_b32 v91, v173, v91
	ds_bpermute_b32 v92, v173, v92
	ds_bpermute_b32 v93, v173, v93
	s_waitcnt lgkmcnt(0)
	global_store_dwordx4 v[98:99], v[90:93], off
	v_cvt_pk_bf16_f32 v74, v74, v75
	v_add_f32_e32 v75, 1.0, v78
	v_rcp_f32_e32 v75, v75
	v_add_f32_e32 v78, 1.0, v79
	v_rcp_f32_e32 v78, v78
	v_mul_f32_e32 v76, v76, v80
	v_mul_f32_e32 v75, v76, v75
	v_mul_f32_e32 v76, v77, v81
	v_mul_f32_e32 v77, 0xbfb8aa3b, v70
	v_mul_f32_e32 v76, v76, v78
	v_exp_f32_e32 v77, v77
	v_mul_f32_e32 v78, 0xbfb8aa3b, v71
	v_exp_f32_e32 v78, v78
	v_cvt_pk_bf16_f32 v75, v75, v76
	v_add_f32_e32 v76, 1.0, v77
	v_rcp_f32_e32 v76, v76
	v_add_f32_e32 v77, 1.0, v78
	v_mul_f32_e32 v66, v66, v70
	v_mul_f32_e32 v70, 0xbfb8aa3b, v72
	v_rcp_f32_e32 v77, v77
	v_mul_f32_e32 v67, v67, v71
	v_exp_f32_e32 v70, v70
	v_mul_f32_e32 v71, 0xbfb8aa3b, v73
	v_exp_f32_e32 v71, v71
	v_mul_f32_e32 v66, v66, v76
	v_mul_f32_e32 v67, v67, v77
	v_cvt_pk_bf16_f32 v76, v66, v67
	v_add_f32_e32 v66, 1.0, v70
	v_rcp_f32_e32 v66, v66
	v_add_f32_e32 v67, 1.0, v71
	v_rcp_f32_e32 v67, v67
	v_mul_f32_e32 v68, v68, v72
	v_mul_f32_e32 v66, v68, v66
	v_mul_f32_e32 v68, v69, v73
	v_mul_f32_e32 v67, v68, v67
	v_mul_f32_e32 v68, 0xbfb8aa3b, v62
	v_mul_f32_e32 v69, 0xbfb8aa3b, v63
	v_exp_f32_e32 v68, v68
	v_exp_f32_e32 v69, v69
	v_mul_f32_e32 v58, v58, v62
	v_mul_f32_e32 v62, 0xbfb8aa3b, v64
	v_add_f32_e32 v68, 1.0, v68
	v_add_f32_e32 v69, 1.0, v69
	v_rcp_f32_e32 v68, v68
	v_rcp_f32_e32 v69, v69
	v_mul_f32_e32 v59, v59, v63
	v_exp_f32_e32 v62, v62
	v_mul_f32_e32 v63, 0xbfb8aa3b, v65
	v_or_b32_e32 v82, 48, v156
	v_exp_f32_e32 v63, v63
	v_mad_i64_i32 v[82:83], s[48:49], v82, s63, v[150:151]
	v_lshl_add_u64 v[82:83], v[82:83], 0, v[148:149]
	v_mul_f32_e32 v58, v58, v68
	v_mul_f32_e32 v59, v59, v69
	v_cvt_pk_bf16_f32 v77, v66, v67
	ds_bpermute_b32 v74, v173, v74
	ds_bpermute_b32 v75, v173, v75
	ds_bpermute_b32 v76, v173, v76
	ds_bpermute_b32 v77, v173, v77
	s_waitcnt lgkmcnt(0)
	global_store_dwordx4 v[82:83], v[74:77], off
	v_cvt_pk_bf16_f32 v58, v58, v59
	v_add_f32_e32 v59, 1.0, v62
	v_rcp_f32_e32 v59, v59
	v_add_f32_e32 v62, 1.0, v63
	v_rcp_f32_e32 v62, v62
	v_mul_f32_e32 v60, v60, v64
	v_mul_f32_e32 v59, v60, v59
	v_mul_f32_e32 v60, v61, v65
	v_mul_f32_e32 v61, 0xbfb8aa3b, v54
	v_mul_f32_e32 v60, v60, v62
	v_exp_f32_e32 v61, v61
	v_mul_f32_e32 v62, 0xbfb8aa3b, v55
	v_exp_f32_e32 v62, v62
	v_cvt_pk_bf16_f32 v59, v59, v60
	v_add_f32_e32 v60, 1.0, v61
	v_rcp_f32_e32 v60, v60
	v_add_f32_e32 v61, 1.0, v62
	v_mul_f32_e32 v50, v50, v54
	v_mul_f32_e32 v54, 0xbfb8aa3b, v56
	v_rcp_f32_e32 v61, v61
	v_mul_f32_e32 v51, v51, v55
	v_exp_f32_e32 v54, v54
	v_mul_f32_e32 v55, 0xbfb8aa3b, v57
	v_exp_f32_e32 v55, v55
	v_mul_f32_e32 v50, v50, v60
	v_mul_f32_e32 v51, v51, v61
	v_cvt_pk_bf16_f32 v60, v50, v51
	v_add_f32_e32 v50, 1.0, v54
	v_rcp_f32_e32 v50, v50
	v_add_f32_e32 v51, 1.0, v55
	v_rcp_f32_e32 v51, v51
	v_mul_f32_e32 v52, v52, v56
	v_mul_f32_e32 v50, v52, v50
	v_mul_f32_e32 v52, v53, v57
	v_mul_f32_e32 v51, v52, v51
	v_mul_f32_e32 v52, 0xbfb8aa3b, v46
	v_mul_f32_e32 v53, 0xbfb8aa3b, v47
	v_exp_f32_e32 v52, v52
	v_exp_f32_e32 v53, v53
	v_mul_f32_e32 v42, v42, v46
	v_mul_f32_e32 v46, 0xbfb8aa3b, v48
	v_add_f32_e32 v52, 1.0, v52
	v_add_f32_e32 v53, 1.0, v53
	v_rcp_f32_e32 v52, v52
	v_rcp_f32_e32 v53, v53
	v_mul_f32_e32 v43, v43, v47
	v_exp_f32_e32 v46, v46
	v_mul_f32_e32 v47, 0xbfb8aa3b, v49
	v_add_u32_e32 v66, 0x80, v156
	v_exp_f32_e32 v47, v47
	v_mad_i64_i32 v[66:67], s[48:49], v66, s63, v[150:151]
	v_lshl_add_u64 v[66:67], v[66:67], 0, v[148:149]
	v_mul_f32_e32 v42, v42, v52
	v_mul_f32_e32 v43, v43, v53
	v_cvt_pk_bf16_f32 v61, v50, v51
	ds_bpermute_b32 v58, v173, v58
	ds_bpermute_b32 v59, v173, v59
	ds_bpermute_b32 v60, v173, v60
	ds_bpermute_b32 v61, v173, v61
	s_waitcnt lgkmcnt(0)
; __device__ __forceinline__ unsigned cvt_pk_bf16(float lo, float hi) { unsigned r; asm volatile("v_cvt_pk_bf16_f32 %0, %1, %2" : "=v"(r) : "v"(lo), "v"(hi)); return r; }
; #define PG8_BAR __builtin_amdgcn_s_barrier()
; template <class Epi, class Sched, bool ALIGN_EPI = false, bool SP2 = false>
; __device__ __forceinline__ void gemm_phase(PG8_LAS unsigned char* lds, const Gemm g, const Sched& S, const Epi& E) {
;     ...
;         if (!has_next) break;
; #pragma unroll
;         for (int a = 0; a < 2; ++a)
; #pragma unroll
;             for (int b = 0; b < 2; ++b)
; #pragma unroll
;                 for (int m = 0; m < 4; ++m)
; #pragma unroll
;                     for (int n = 0; n < 2; ++n) acc[a][b][m][n] = (f32x4){0.f, 0.f, 0.f, 0.f};
;         cur = nxt; cA = nA; cB = nB; ++ui;
;         if constexpr (ALIGN_EPI) { if (wr == 1) PG8_BAR; }
; __device__ __forceinline__ float silu_mul(float g, float u) { return g * u * __builtin_amdgcn_rcpf(1.f + __builtin_amdgcn_exp2f(-1.4426950408889634f * g)); }
;     __device__ __forceinline__ void operator()(const f32x4 (&acc)[2][2][4][2], const Unit& u, int wr, int wc, int fr, int fq) const {
;         const int row0 = u.pm * BM + wr * 64 + fr, col0 = u.pn * HALF + wc * 32 + 8 * fq;
; #pragma unroll
;         for (int ai = 0; ai < 2; ++ai)
; #pragma unroll
;             for (int m = 0; m < 4; ++m) { bf16_t* rowp = O + (size_t)(row0 + ai * HALF + m * 16) * ldc + col0;
;                 const f32x4 g0 = acc[ai][0][m][0], g1 = acc[ai][0][m][1], u0 = acc[ai][1][m][0], u1 = acc[ai][1][m][1];
;                 u32x4 w; w.x = cvt_pk_bf16(silu_mul(g0[0], u0[0]), silu_mul(g0[1], u0[1])); w.y = cvt_pk_bf16(silu_mul(g0[2], u0[2]), silu_mul(g0[3], u0[3]));
;                 w.z = cvt_pk_bf16(silu_mul(g1[0], u1[0]), silu_mul(g1[1], u1[1])); w.w = cvt_pk_bf16(silu_mul(g1[2], u1[2]), silu_mul(g1[3], u1[3]));
;                 *(u32x4*)rowp = w; }
	global_store_dwordx4 v[66:67], v[58:61], off
	v_cvt_pk_bf16_f32 v42, v42, v43
	v_add_f32_e32 v43, 1.0, v46
	v_rcp_f32_e32 v43, v43
	v_add_f32_e32 v46, 1.0, v47
	v_rcp_f32_e32 v46, v46
	v_mul_f32_e32 v44, v44, v48
	v_mul_f32_e32 v43, v44, v43
	v_mul_f32_e32 v44, v45, v49
	v_mul_f32_e32 v45, 0xbfb8aa3b, v38
	v_mul_f32_e32 v44, v44, v46
	v_exp_f32_e32 v45, v45
	v_mul_f32_e32 v46, 0xbfb8aa3b, v39
	v_exp_f32_e32 v46, v46
	v_cvt_pk_bf16_f32 v43, v43, v44
	v_add_f32_e32 v44, 1.0, v45
	v_rcp_f32_e32 v44, v44
	v_add_f32_e32 v45, 1.0, v46
	v_mul_f32_e32 v34, v34, v38
	v_mul_f32_e32 v38, 0xbfb8aa3b, v40
	v_rcp_f32_e32 v45, v45
	v_mul_f32_e32 v35, v35, v39
	v_exp_f32_e32 v38, v38
	v_mul_f32_e32 v39, 0xbfb8aa3b, v41
	v_exp_f32_e32 v39, v39
	v_mul_f32_e32 v34, v34, v44
	v_mul_f32_e32 v35, v35, v45
	v_cvt_pk_bf16_f32 v44, v34, v35
	v_add_f32_e32 v34, 1.0, v38
	v_rcp_f32_e32 v34, v34
	v_add_f32_e32 v35, 1.0, v39
	v_rcp_f32_e32 v35, v35
	v_mul_f32_e32 v36, v36, v40
	v_mul_f32_e32 v34, v36, v34
	v_mul_f32_e32 v36, v37, v41
	v_mul_f32_e32 v35, v36, v35
	v_mul_f32_e32 v36, 0xbfb8aa3b, v30
	v_mul_f32_e32 v37, 0xbfb8aa3b, v31
	v_exp_f32_e32 v36, v36
	v_exp_f32_e32 v37, v37
	v_mul_f32_e32 v26, v26, v30
	v_mul_f32_e32 v30, 0xbfb8aa3b, v32
	v_add_f32_e32 v36, 1.0, v36
	v_add_f32_e32 v37, 1.0, v37
	v_rcp_f32_e32 v36, v36
	v_rcp_f32_e32 v37, v37
	v_mul_f32_e32 v27, v27, v31
	v_exp_f32_e32 v30, v30
	v_mul_f32_e32 v31, 0xbfb8aa3b, v33
	v_add_u32_e32 v50, 0x90, v156
	v_exp_f32_e32 v31, v31
	v_mad_i64_i32 v[50:51], s[48:49], v50, s63, v[150:151]
	v_lshl_add_u64 v[50:51], v[50:51], 0, v[148:149]
	v_mul_f32_e32 v26, v26, v36
	v_mul_f32_e32 v27, v27, v37
	v_cvt_pk_bf16_f32 v45, v34, v35
	ds_bpermute_b32 v42, v173, v42
	ds_bpermute_b32 v43, v173, v43
	ds_bpermute_b32 v44, v173, v44
	ds_bpermute_b32 v45, v173, v45
	s_waitcnt lgkmcnt(0)
	global_store_dwordx4 v[50:51], v[42:45], off
	v_cvt_pk_bf16_f32 v26, v26, v27
	v_add_f32_e32 v27, 1.0, v30
	v_rcp_f32_e32 v27, v27
	v_add_f32_e32 v30, 1.0, v31
	v_rcp_f32_e32 v30, v30
	v_mul_f32_e32 v28, v28, v32
	v_mul_f32_e32 v27, v28, v27
	v_mul_f32_e32 v28, v29, v33
	v_mul_f32_e32 v29, 0xbfb8aa3b, v22
	v_mul_f32_e32 v28, v28, v30
	v_exp_f32_e32 v29, v29
	v_mul_f32_e32 v30, 0xbfb8aa3b, v23
	v_exp_f32_e32 v30, v30
	v_cvt_pk_bf16_f32 v27, v27, v28
	v_add_f32_e32 v28, 1.0, v29
	v_rcp_f32_e32 v28, v28
	v_add_f32_e32 v29, 1.0, v30
	v_mul_f32_e32 v18, v18, v22
	v_mul_f32_e32 v22, 0xbfb8aa3b, v24
	v_rcp_f32_e32 v29, v29
	v_mul_f32_e32 v19, v19, v23
	v_exp_f32_e32 v22, v22
	v_mul_f32_e32 v23, 0xbfb8aa3b, v25
	v_exp_f32_e32 v23, v23
	v_mul_f32_e32 v18, v18, v28
	v_mul_f32_e32 v19, v19, v29
	v_cvt_pk_bf16_f32 v28, v18, v19
	v_add_f32_e32 v18, 1.0, v22
	v_rcp_f32_e32 v18, v18
	v_add_f32_e32 v19, 1.0, v23
	v_rcp_f32_e32 v19, v19
	v_mul_f32_e32 v20, v20, v24
	v_mul_f32_e32 v18, v20, v18
	v_mul_f32_e32 v20, v21, v25
	v_mul_f32_e32 v19, v20, v19
	v_mul_f32_e32 v20, 0xbfb8aa3b, v14
	v_mul_f32_e32 v21, 0xbfb8aa3b, v15
	v_exp_f32_e32 v20, v20
	v_exp_f32_e32 v21, v21
	v_mul_f32_e32 v10, v10, v14
	v_mul_f32_e32 v14, 0xbfb8aa3b, v16
	v_add_f32_e32 v20, 1.0, v20
	v_add_f32_e32 v21, 1.0, v21
	v_rcp_f32_e32 v20, v20
	v_rcp_f32_e32 v21, v21
	v_mul_f32_e32 v11, v11, v15
	v_exp_f32_e32 v14, v14
	v_mul_f32_e32 v15, 0xbfb8aa3b, v17
	v_add_u32_e32 v34, 0xa0, v156
	v_exp_f32_e32 v15, v15
	v_mad_i64_i32 v[34:35], s[48:49], v34, s63, v[150:151]
	v_lshl_add_u64 v[34:35], v[34:35], 0, v[148:149]
	v_mul_f32_e32 v10, v10, v20
	v_mul_f32_e32 v11, v11, v21
	v_cvt_pk_bf16_f32 v29, v18, v19
	ds_bpermute_b32 v26, v173, v26
	ds_bpermute_b32 v27, v173, v27
	ds_bpermute_b32 v28, v173, v28
	ds_bpermute_b32 v29, v173, v29
	s_waitcnt lgkmcnt(0)
	global_store_dwordx4 v[34:35], v[26:29], off
	v_cvt_pk_bf16_f32 v10, v10, v11
	v_add_f32_e32 v11, 1.0, v14
	v_rcp_f32_e32 v11, v11
	v_add_f32_e32 v14, 1.0, v15
	v_rcp_f32_e32 v14, v14
	v_mul_f32_e32 v12, v12, v16
	v_mul_f32_e32 v11, v12, v11
	v_mul_f32_e32 v12, v13, v17
	v_mul_f32_e32 v13, 0xbfb8aa3b, v6
	v_mul_f32_e32 v12, v12, v14
	v_exp_f32_e32 v13, v13
	v_mul_f32_e32 v14, 0xbfb8aa3b, v7
	v_exp_f32_e32 v14, v14
	v_cvt_pk_bf16_f32 v11, v11, v12
	v_add_f32_e32 v12, 1.0, v13
	v_rcp_f32_e32 v12, v12
	v_add_f32_e32 v13, 1.0, v14
	v_mul_f32_e32 v2, v2, v6
	v_mul_f32_e32 v6, 0xbfb8aa3b, v8
	v_rcp_f32_e32 v13, v13
	v_mul_f32_e32 v3, v3, v7
	v_exp_f32_e32 v6, v6
	v_mul_f32_e32 v7, 0xbfb8aa3b, v9
	v_exp_f32_e32 v7, v7
	v_mul_f32_e32 v2, v2, v12
	v_mul_f32_e32 v3, v3, v13
	v_cvt_pk_bf16_f32 v12, v2, v3
	v_add_f32_e32 v2, 1.0, v6
	v_rcp_f32_e32 v2, v2
	v_add_f32_e32 v3, 1.0, v7
	v_rcp_f32_e32 v3, v3
	v_add_u32_e32 v18, 0xb0, v156
	v_mad_i64_i32 v[18:19], s[48:49], v18, s63, v[150:151]
	v_mul_f32_e32 v4, v4, v8
	v_lshl_add_u64 v[18:19], v[18:19], 0, v[148:149]
	v_mul_f32_e32 v2, v4, v2
	v_mul_f32_e32 v4, v5, v9
	s_andn2_b64 vcc, exec, s[4:5]
	s_mov_b64 s[4:5], -1
	v_mul_f32_e32 v3, v4, v3
	v_cvt_pk_bf16_f32 v13, v2, v3
	ds_bpermute_b32 v10, v173, v10
	ds_bpermute_b32 v11, v173, v11
	ds_bpermute_b32 v12, v173, v12
	ds_bpermute_b32 v13, v173, v13
	s_waitcnt lgkmcnt(0)
	global_store_dwordx4 v[18:19], v[10:13], off
	s_cbranch_vccnz .LBB0_62
	s_andn2_b64 vcc, exec, s[14:15]
	s_cbranch_vccnz .LBB0_61
	s_barrier
	s_branch .LBB0_61

; __device__ __forceinline__ unsigned cvt_pk_bf16(float lo, float hi) { unsigned r; asm volatile("v_cvt_pk_bf16_f32 %0, %1, %2" : "=v"(r) : "v"(lo), "v"(hi)); return r; }
; __device__ __forceinline__ float silu_mul(float g, float u) { return g * u * __builtin_amdgcn_rcpf(1.f + __builtin_amdgcn_exp2f(-1.4426950408889634f * g)); }
;     __device__ __forceinline__ void operator()(const f32x4 (&acc)[2][2][4][2], const Unit& u, int wr, int wc, int fr, int fq) const {
;         const int row0 = u.pm * BM + wr * 64 + fr, col0 = u.pn * HALF + wc * 32 + 8 * fq;
; #pragma unroll
;         for (int ai = 0; ai < 2; ++ai)
; #pragma unroll
;             for (int m = 0; m < 4; ++m) { bf16_t* rowp = O + (size_t)(row0 + ai * HALF + m * 16) * ldc + col0;
;                 const f32x4 g0 = acc[ai][0][m][0], g1 = acc[ai][0][m][1], u0 = acc[ai][1][m][0], u1 = acc[ai][1][m][1];
;                 u32x4 w; w.x = cvt_pk_bf16(silu_mul(g0[0], u0[0]), silu_mul(g0[1], u0[1])); w.y = cvt_pk_bf16(silu_mul(g0[2], u0[2]), silu_mul(g0[3], u0[3]));
;                 w.z = cvt_pk_bf16(silu_mul(g1[0], u1[0]), silu_mul(g1[1], u1[1])); w.w = cvt_pk_bf16(silu_mul(g1[2], u1[2]), silu_mul(g1[3], u1[3]));
;                 *(u32x4*)rowp = w; }
.LBB0_1221:
	v_mul_f32_e32 v157, 0xbfb8aa3b, v126
	v_mul_f32_e32 v160, 0xbfb8aa3b, v127
	v_exp_f32_e32 v157, v157
	v_exp_f32_e32 v160, v160
	v_mul_f32_e32 v122, v122, v126
	v_mul_f32_e32 v126, 0xbfb8aa3b, v128
	v_add_f32_e32 v157, 1.0, v157
	v_add_f32_e32 v160, 1.0, v160
	v_rcp_f32_e32 v157, v157
	v_rcp_f32_e32 v160, v160
	v_mul_f32_e32 v123, v123, v127
	v_exp_f32_e32 v126, v126
	v_mul_f32_e32 v127, 0xbfb8aa3b, v129
	v_exp_f32_e32 v127, v127
	v_mul_f32_e32 v122, v122, v157
	v_mul_f32_e32 v123, v123, v160
	v_cvt_pk_bf16_f32 v122, v122, v123
	v_add_f32_e32 v123, 1.0, v126
	v_rcp_f32_e32 v123, v123
	v_add_f32_e32 v126, 1.0, v127
	v_rcp_f32_e32 v126, v126
	v_mul_f32_e32 v124, v124, v128
	v_mul_f32_e32 v123, v124, v123
	v_mul_f32_e32 v124, v125, v129
	v_mul_f32_e32 v125, 0xbfb8aa3b, v118
	v_mul_f32_e32 v124, v124, v126
	v_exp_f32_e32 v125, v125
	v_mul_f32_e32 v126, 0xbfb8aa3b, v119
	v_exp_f32_e32 v126, v126
	v_cvt_pk_bf16_f32 v123, v123, v124
	v_add_f32_e32 v124, 1.0, v125
	v_rcp_f32_e32 v124, v124
	v_add_f32_e32 v125, 1.0, v126
	v_mul_f32_e32 v114, v114, v118
	v_mul_f32_e32 v118, 0xbfb8aa3b, v120
	v_rcp_f32_e32 v125, v125
	v_mul_f32_e32 v115, v115, v119
	v_exp_f32_e32 v118, v118
	v_mul_f32_e32 v119, 0xbfb8aa3b, v121
	v_exp_f32_e32 v119, v119
	v_mul_f32_e32 v114, v114, v124
	v_mul_f32_e32 v115, v115, v125
	v_cvt_pk_bf16_f32 v124, v114, v115
	v_add_f32_e32 v114, 1.0, v118
	v_rcp_f32_e32 v114, v114
	v_add_f32_e32 v115, 1.0, v119
	v_rcp_f32_e32 v115, v115
	v_mul_f32_e32 v116, v116, v120
	v_mul_f32_e32 v114, v116, v114
	v_mul_f32_e32 v116, v117, v121
	v_mul_f32_e32 v115, v116, v115
	v_mul_f32_e32 v116, 0xbfb8aa3b, v110
	v_mul_f32_e32 v117, 0xbfb8aa3b, v111
	v_exp_f32_e32 v116, v116
	v_exp_f32_e32 v117, v117
	v_mul_f32_e32 v106, v106, v110
	v_mul_f32_e32 v110, 0xbfb8aa3b, v112
	v_add_f32_e32 v116, 1.0, v116
	v_add_f32_e32 v117, 1.0, v117
	v_rcp_f32_e32 v116, v116
	v_rcp_f32_e32 v117, v117
	v_mbcnt_lo_u32_b32 v168, -1, 0
	v_mbcnt_hi_u32_b32 v168, -1, v168
	v_lshrrev_b32_e32 v169, 2, v168
	v_and_b32_e32 v170, 3, v168
	v_and_b32_e32 v171, -16, v1
	v_or_b32_e32 v171, v171, v169
	v_and_b32_e32 v172, 0xffffffe7, v152
	v_lshl_or_b32 v172, v170, 3, v172
	v_lshl_or_b32 v173, v170, 4, v169
	v_lshlrev_b32_e32 v173, 2, v173
	v_lshl_or_b32 v148, s61, 7, v172
	v_mul_f32_e32 v107, v107, v111
	v_exp_f32_e32 v110, v110
	v_mul_f32_e32 v111, 0xbfb8aa3b, v113
	v_lshl_add_u32 v156, s44, 8, v171
	v_ashrrev_i32_e32 v149, 31, v148
	v_mov_b64_e32 v[150:151], s[14:15]
	v_exp_f32_e32 v111, v111
	v_mad_i64_i32 v[158:159], s[46:47], v156, s60, v[150:151]
	v_lshlrev_b64 v[148:149], 1, v[148:149]
	v_lshl_add_u64 v[158:159], v[158:159], 0, v[148:149]
	v_mul_f32_e32 v106, v106, v116
	v_mul_f32_e32 v107, v107, v117
	v_cvt_pk_bf16_f32 v125, v114, v115
	ds_bpermute_b32 v122, v173, v122
	ds_bpermute_b32 v123, v173, v123
	ds_bpermute_b32 v124, v173, v124
	ds_bpermute_b32 v125, v173, v125
	s_waitcnt lgkmcnt(0)
	global_store_dwordx4 v[158:159], v[122:125], off
	v_cvt_pk_bf16_f32 v106, v106, v107
	v_add_f32_e32 v107, 1.0, v110
	v_rcp_f32_e32 v107, v107
	v_add_f32_e32 v110, 1.0, v111
	v_rcp_f32_e32 v110, v110
	v_mul_f32_e32 v108, v108, v112
	v_mul_f32_e32 v107, v108, v107
	v_mul_f32_e32 v108, v109, v113
	v_mul_f32_e32 v109, 0xbfb8aa3b, v102
	v_mul_f32_e32 v108, v108, v110
	v_exp_f32_e32 v109, v109
	v_mul_f32_e32 v110, 0xbfb8aa3b, v103
	v_exp_f32_e32 v110, v110
	v_cvt_pk_bf16_f32 v107, v107, v108
	v_add_f32_e32 v108, 1.0, v109
	v_rcp_f32_e32 v108, v108
	v_add_f32_e32 v109, 1.0, v110
	v_mul_f32_e32 v98, v98, v102
	v_mul_f32_e32 v102, 0xbfb8aa3b, v104
	v_rcp_f32_e32 v109, v109
	v_mul_f32_e32 v99, v99, v103
	v_exp_f32_e32 v102, v102
	v_mul_f32_e32 v103, 0xbfb8aa3b, v105
	v_exp_f32_e32 v103, v103
	v_mul_f32_e32 v98, v98, v108
	v_mul_f32_e32 v99, v99, v109
	v_cvt_pk_bf16_f32 v108, v98, v99
	v_add_f32_e32 v98, 1.0, v102
	v_rcp_f32_e32 v98, v98
	v_add_f32_e32 v99, 1.0, v103
	v_rcp_f32_e32 v99, v99
	v_mul_f32_e32 v100, v100, v104
	v_mul_f32_e32 v98, v100, v98
	v_mul_f32_e32 v100, v101, v105
	v_mul_f32_e32 v99, v100, v99
	v_mul_f32_e32 v100, 0xbfb8aa3b, v94
	v_mul_f32_e32 v101, 0xbfb8aa3b, v95
	v_exp_f32_e32 v100, v100
	v_exp_f32_e32 v101, v101
	v_mul_f32_e32 v90, v90, v94
	v_mul_f32_e32 v94, 0xbfb8aa3b, v96
	v_add_f32_e32 v100, 1.0, v100
	v_add_f32_e32 v101, 1.0, v101
	v_rcp_f32_e32 v100, v100
	v_rcp_f32_e32 v101, v101
	v_mul_f32_e32 v91, v91, v95
	v_exp_f32_e32 v94, v94
	v_mul_f32_e32 v95, 0xbfb8aa3b, v97
	v_or_b32_e32 v114, 16, v156
	v_exp_f32_e32 v95, v95
	v_mad_i64_i32 v[114:115], s[46:47], v114, s60, v[150:151]
	v_lshl_add_u64 v[114:115], v[114:115], 0, v[148:149]
	v_mul_f32_e32 v90, v90, v100
	v_mul_f32_e32 v91, v91, v101
	v_cvt_pk_bf16_f32 v109, v98, v99
	ds_bpermute_b32 v106, v173, v106
	ds_bpermute_b32 v107, v173, v107
	ds_bpermute_b32 v108, v173, v108
	ds_bpermute_b32 v109, v173, v109
	s_waitcnt lgkmcnt(0)
; __device__ __forceinline__ unsigned cvt_pk_bf16(float lo, float hi) { unsigned r; asm volatile("v_cvt_pk_bf16_f32 %0, %1, %2" : "=v"(r) : "v"(lo), "v"(hi)); return r; }
; __device__ __forceinline__ float silu_mul(float g, float u) { return g * u * __builtin_amdgcn_rcpf(1.f + __builtin_amdgcn_exp2f(-1.4426950408889634f * g)); }
;     __device__ __forceinline__ void operator()(const f32x4 (&acc)[2][2][4][2], const Unit& u, int wr, int wc, int fr, int fq) const {
;         const int row0 = u.pm * BM + wr * 64 + fr, col0 = u.pn * HALF + wc * 32 + 8 * fq;
; #pragma unroll
;         for (int ai = 0; ai < 2; ++ai)
; #pragma unroll
;             for (int m = 0; m < 4; ++m) { bf16_t* rowp = O + (size_t)(row0 + ai * HALF + m * 16) * ldc + col0;
;                 const f32x4 g0 = acc[ai][0][m][0], g1 = acc[ai][0][m][1], u0 = acc[ai][1][m][0], u1 = acc[ai][1][m][1];
;                 u32x4 w; w.x = cvt_pk_bf16(silu_mul(g0[0], u0[0]), silu_mul(g0[1], u0[1])); w.y = cvt_pk_bf16(silu_mul(g0[2], u0[2]), silu_mul(g0[3], u0[3]));
;                 w.z = cvt_pk_bf16(silu_mul(g1[0], u1[0]), silu_mul(g1[1], u1[1])); w.w = cvt_pk_bf16(silu_mul(g1[2], u1[2]), silu_mul(g1[3], u1[3]));
;                 *(u32x4*)rowp = w; }
	global_store_dwordx4 v[114:115], v[106:109], off
	v_cvt_pk_bf16_f32 v90, v90, v91
	v_add_f32_e32 v91, 1.0, v94
	v_rcp_f32_e32 v91, v91
	v_add_f32_e32 v94, 1.0, v95
	v_rcp_f32_e32 v94, v94
	v_mul_f32_e32 v92, v92, v96
	v_mul_f32_e32 v91, v92, v91
	v_mul_f32_e32 v92, v93, v97
	v_mul_f32_e32 v93, 0xbfb8aa3b, v86
	v_mul_f32_e32 v92, v92, v94
	v_exp_f32_e32 v93, v93
	v_mul_f32_e32 v94, 0xbfb8aa3b, v87
	v_exp_f32_e32 v94, v94
	v_cvt_pk_bf16_f32 v91, v91, v92
	v_add_f32_e32 v92, 1.0, v93
	v_rcp_f32_e32 v92, v92
	v_add_f32_e32 v93, 1.0, v94
	v_mul_f32_e32 v82, v82, v86
	v_mul_f32_e32 v86, 0xbfb8aa3b, v88
	v_rcp_f32_e32 v93, v93
	v_mul_f32_e32 v83, v83, v87
	v_exp_f32_e32 v86, v86
	v_mul_f32_e32 v87, 0xbfb8aa3b, v89
	v_exp_f32_e32 v87, v87
	v_mul_f32_e32 v82, v82, v92
	v_mul_f32_e32 v83, v83, v93
	v_cvt_pk_bf16_f32 v92, v82, v83
	v_add_f32_e32 v82, 1.0, v86
	v_rcp_f32_e32 v82, v82
	v_add_f32_e32 v83, 1.0, v87
	v_rcp_f32_e32 v83, v83
	v_mul_f32_e32 v84, v84, v88
	v_mul_f32_e32 v82, v84, v82
	v_mul_f32_e32 v84, v85, v89
	v_mul_f32_e32 v83, v84, v83
	v_mul_f32_e32 v84, 0xbfb8aa3b, v78
	v_mul_f32_e32 v85, 0xbfb8aa3b, v79
	v_exp_f32_e32 v84, v84
	v_exp_f32_e32 v85, v85
	v_mul_f32_e32 v74, v74, v78
	v_mul_f32_e32 v78, 0xbfb8aa3b, v80
	v_add_f32_e32 v84, 1.0, v84
	v_add_f32_e32 v85, 1.0, v85
	v_rcp_f32_e32 v84, v84
	v_rcp_f32_e32 v85, v85
	v_mul_f32_e32 v75, v75, v79
	v_exp_f32_e32 v78, v78
	v_mul_f32_e32 v79, 0xbfb8aa3b, v81
	v_or_b32_e32 v98, 32, v156
	v_exp_f32_e32 v79, v79
	v_mad_i64_i32 v[98:99], s[46:47], v98, s60, v[150:151]
	v_lshl_add_u64 v[98:99], v[98:99], 0, v[148:149]
	v_mul_f32_e32 v74, v74, v84
	v_mul_f32_e32 v75, v75, v85
	v_cvt_pk_bf16_f32 v93, v82, v83
	ds_bpermute_b32 v90, v173, v90
	ds_bpermute_b32 v91, v173, v91
	ds_bpermute_b32 v92, v173, v92
	ds_bpermute_b32 v93, v173, v93
	s_waitcnt lgkmcnt(0)
	global_store_dwordx4 v[98:99], v[90:93], off
	v_cvt_pk_bf16_f32 v74, v74, v75
	v_add_f32_e32 v75, 1.0, v78
	v_rcp_f32_e32 v75, v75
	v_add_f32_e32 v78, 1.0, v79
	v_rcp_f32_e32 v78, v78
	v_mul_f32_e32 v76, v76, v80
	v_mul_f32_e32 v75, v76, v75
	v_mul_f32_e32 v76, v77, v81
	v_mul_f32_e32 v77, 0xbfb8aa3b, v70
	v_mul_f32_e32 v76, v76, v78
	v_exp_f32_e32 v77, v77
	v_mul_f32_e32 v78, 0xbfb8aa3b, v71
	v_exp_f32_e32 v78, v78
	v_cvt_pk_bf16_f32 v75, v75, v76
	v_add_f32_e32 v76, 1.0, v77
	v_rcp_f32_e32 v76, v76
	v_add_f32_e32 v77, 1.0, v78
	v_mul_f32_e32 v66, v66, v70
	v_mul_f32_e32 v70, 0xbfb8aa3b, v72
	v_rcp_f32_e32 v77, v77
	v_mul_f32_e32 v67, v67, v71
	v_exp_f32_e32 v70, v70
	v_mul_f32_e32 v71, 0xbfb8aa3b, v73
	v_exp_f32_e32 v71, v71
	v_mul_f32_e32 v66, v66, v76
	v_mul_f32_e32 v67, v67, v77
	v_cvt_pk_bf16_f32 v76, v66, v67
	v_add_f32_e32 v66, 1.0, v70
	v_rcp_f32_e32 v66, v66
	v_add_f32_e32 v67, 1.0, v71
	v_rcp_f32_e32 v67, v67
	v_mul_f32_e32 v68, v68, v72
	v_mul_f32_e32 v66, v68, v66
	v_mul_f32_e32 v68, v69, v73
	v_mul_f32_e32 v67, v68, v67
	v_mul_f32_e32 v68, 0xbfb8aa3b, v62
	v_mul_f32_e32 v69, 0xbfb8aa3b, v63
	v_exp_f32_e32 v68, v68
	v_exp_f32_e32 v69, v69
	v_mul_f32_e32 v58, v58, v62
	v_mul_f32_e32 v62, 0xbfb8aa3b, v64
	v_add_f32_e32 v68, 1.0, v68
	v_add_f32_e32 v69, 1.0, v69
	v_rcp_f32_e32 v68, v68
	v_rcp_f32_e32 v69, v69
	v_mul_f32_e32 v59, v59, v63
	v_exp_f32_e32 v62, v62
	v_mul_f32_e32 v63, 0xbfb8aa3b, v65
	v_or_b32_e32 v82, 48, v156
	v_exp_f32_e32 v63, v63
	v_mad_i64_i32 v[82:83], s[46:47], v82, s60, v[150:151]
	v_lshl_add_u64 v[82:83], v[82:83], 0, v[148:149]
	v_mul_f32_e32 v58, v58, v68
	v_mul_f32_e32 v59, v59, v69
	v_cvt_pk_bf16_f32 v77, v66, v67
	ds_bpermute_b32 v74, v173, v74
	ds_bpermute_b32 v75, v173, v75
	ds_bpermute_b32 v76, v173, v76
	ds_bpermute_b32 v77, v173, v77
	s_waitcnt lgkmcnt(0)
	global_store_dwordx4 v[82:83], v[74:77], off
	v_cvt_pk_bf16_f32 v58, v58, v59
	v_add_f32_e32 v59, 1.0, v62
	v_rcp_f32_e32 v59, v59
	v_add_f32_e32 v62, 1.0, v63
	v_rcp_f32_e32 v62, v62
	v_mul_f32_e32 v60, v60, v64
	v_mul_f32_e32 v59, v60, v59
	v_mul_f32_e32 v60, v61, v65
	v_mul_f32_e32 v61, 0xbfb8aa3b, v54
	v_mul_f32_e32 v60, v60, v62
	v_exp_f32_e32 v61, v61
	v_mul_f32_e32 v62, 0xbfb8aa3b, v55
	v_exp_f32_e32 v62, v62
	v_cvt_pk_bf16_f32 v59, v59, v60
	v_add_f32_e32 v60, 1.0, v61
	v_rcp_f32_e32 v60, v60
	v_add_f32_e32 v61, 1.0, v62
	v_mul_f32_e32 v50, v50, v54
	v_mul_f32_e32 v54, 0xbfb8aa3b, v56
	v_rcp_f32_e32 v61, v61
	v_mul_f32_e32 v51, v51, v55
	v_exp_f32_e32 v54, v54
	v_mul_f32_e32 v55, 0xbfb8aa3b, v57
	v_exp_f32_e32 v55, v55
	v_mul_f32_e32 v50, v50, v60
	v_mul_f32_e32 v51, v51, v61
	v_cvt_pk_bf16_f32 v60, v50, v51
	v_add_f32_e32 v50, 1.0, v54
	v_rcp_f32_e32 v50, v50
	v_add_f32_e32 v51, 1.0, v55
	v_rcp_f32_e32 v51, v51
	v_mul_f32_e32 v52, v52, v56
	v_mul_f32_e32 v50, v52, v50
	v_mul_f32_e32 v52, v53, v57
	v_mul_f32_e32 v51, v52, v51
	v_mul_f32_e32 v52, 0xbfb8aa3b, v46
	v_mul_f32_e32 v53, 0xbfb8aa3b, v47
	v_exp_f32_e32 v52, v52
	v_exp_f32_e32 v53, v53
	v_mul_f32_e32 v42, v42, v46
	v_mul_f32_e32 v46, 0xbfb8aa3b, v48
	v_add_f32_e32 v52, 1.0, v52
	v_add_f32_e32 v53, 1.0, v53
	v_rcp_f32_e32 v52, v52
	v_rcp_f32_e32 v53, v53
	v_mul_f32_e32 v43, v43, v47
	v_exp_f32_e32 v46, v46
	v_mul_f32_e32 v47, 0xbfb8aa3b, v49
	v_add_u32_e32 v66, 0x80, v156
	v_exp_f32_e32 v47, v47
	v_mad_i64_i32 v[66:67], s[46:47], v66, s60, v[150:151]
	v_lshl_add_u64 v[66:67], v[66:67], 0, v[148:149]
	v_mul_f32_e32 v42, v42, v52
	v_mul_f32_e32 v43, v43, v53
	v_cvt_pk_bf16_f32 v61, v50, v51
	ds_bpermute_b32 v58, v173, v58
	ds_bpermute_b32 v59, v173, v59
	ds_bpermute_b32 v60, v173, v60
	ds_bpermute_b32 v61, v173, v61
	s_waitcnt lgkmcnt(0)
; __device__ __forceinline__ unsigned cvt_pk_bf16(float lo, float hi) { unsigned r; asm volatile("v_cvt_pk_bf16_f32 %0, %1, %2" : "=v"(r) : "v"(lo), "v"(hi)); return r; }
; #define PG8_BAR __builtin_amdgcn_s_barrier()
; template <class Epi, class Sched, bool ALIGN_EPI = false, bool SP2 = false>
; __device__ __forceinline__ void gemm_phase(PG8_LAS unsigned char* lds, const Gemm g, const Sched& S, const Epi& E) {
;     ...
;         if (!has_next) break;
; #pragma unroll
;         for (int a = 0; a < 2; ++a)
; #pragma unroll
;             for (int b = 0; b < 2; ++b)
; #pragma unroll
;                 for (int m = 0; m < 4; ++m)
; #pragma unroll
;                     for (int n = 0; n < 2; ++n) acc[a][b][m][n] = (f32x4){0.f, 0.f, 0.f, 0.f};
;         cur = nxt; cA = nA; cB = nB; ++ui;
;         if constexpr (ALIGN_EPI) { if (wr == 1) PG8_BAR; }
; __device__ __forceinline__ float silu_mul(float g, float u) { return g * u * __builtin_amdgcn_rcpf(1.f + __builtin_amdgcn_exp2f(-1.4426950408889634f * g)); }
;     __device__ __forceinline__ void operator()(const f32x4 (&acc)[2][2][4][2], const Unit& u, int wr, int wc, int fr, int fq) const {
;         const int row0 = u.pm * BM + wr * 64 + fr, col0 = u.pn * HALF + wc * 32 + 8 * fq;
; #pragma unroll
;         for (int ai = 0; ai < 2; ++ai)
; #pragma unroll
;             for (int m = 0; m < 4; ++m) { bf16_t* rowp = O + (size_t)(row0 + ai * HALF + m * 16) * ldc + col0;
;                 const f32x4 g0 = acc[ai][0][m][0], g1 = acc[ai][0][m][1], u0 = acc[ai][1][m][0], u1 = acc[ai][1][m][1];
;                 u32x4 w; w.x = cvt_pk_bf16(silu_mul(g0[0], u0[0]), silu_mul(g0[1], u0[1])); w.y = cvt_pk_bf16(silu_mul(g0[2], u0[2]), silu_mul(g0[3], u0[3]));
;                 w.z = cvt_pk_bf16(silu_mul(g1[0], u1[0]), silu_mul(g1[1], u1[1])); w.w = cvt_pk_bf16(silu_mul(g1[2], u1[2]), silu_mul(g1[3], u1[3]));
;                 *(u32x4*)rowp = w; }
	global_store_dwordx4 v[66:67], v[58:61], off
	v_cvt_pk_bf16_f32 v42, v42, v43
	v_add_f32_e32 v43, 1.0, v46
	v_rcp_f32_e32 v43, v43
	v_add_f32_e32 v46, 1.0, v47
	v_rcp_f32_e32 v46, v46
	v_mul_f32_e32 v44, v44, v48
	v_mul_f32_e32 v43, v44, v43
	v_mul_f32_e32 v44, v45, v49
	v_mul_f32_e32 v45, 0xbfb8aa3b, v38
	v_mul_f32_e32 v44, v44, v46
	v_exp_f32_e32 v45, v45
	v_mul_f32_e32 v46, 0xbfb8aa3b, v39
	v_exp_f32_e32 v46, v46
	v_cvt_pk_bf16_f32 v43, v43, v44
	v_add_f32_e32 v44, 1.0, v45
	v_rcp_f32_e32 v44, v44
	v_add_f32_e32 v45, 1.0, v46
	v_mul_f32_e32 v34, v34, v38
	v_mul_f32_e32 v38, 0xbfb8aa3b, v40
	v_rcp_f32_e32 v45, v45
	v_mul_f32_e32 v35, v35, v39
	v_exp_f32_e32 v38, v38
	v_mul_f32_e32 v39, 0xbfb8aa3b, v41
	v_exp_f32_e32 v39, v39
	v_mul_f32_e32 v34, v34, v44
	v_mul_f32_e32 v35, v35, v45
	v_cvt_pk_bf16_f32 v44, v34, v35
	v_add_f32_e32 v34, 1.0, v38
	v_rcp_f32_e32 v34, v34
	v_add_f32_e32 v35, 1.0, v39
	v_rcp_f32_e32 v35, v35
	v_mul_f32_e32 v36, v36, v40
	v_mul_f32_e32 v34, v36, v34
	v_mul_f32_e32 v36, v37, v41
	v_mul_f32_e32 v35, v36, v35
	v_mul_f32_e32 v36, 0xbfb8aa3b, v30
	v_mul_f32_e32 v37, 0xbfb8aa3b, v31
	v_exp_f32_e32 v36, v36
	v_exp_f32_e32 v37, v37
	v_mul_f32_e32 v26, v26, v30
	v_mul_f32_e32 v30, 0xbfb8aa3b, v32
	v_add_f32_e32 v36, 1.0, v36
	v_add_f32_e32 v37, 1.0, v37
	v_rcp_f32_e32 v36, v36
	v_rcp_f32_e32 v37, v37
	v_mul_f32_e32 v27, v27, v31
	v_exp_f32_e32 v30, v30
	v_mul_f32_e32 v31, 0xbfb8aa3b, v33
	v_add_u32_e32 v50, 0x90, v156
	v_exp_f32_e32 v31, v31
	v_mad_i64_i32 v[50:51], s[46:47], v50, s60, v[150:151]
	v_lshl_add_u64 v[50:51], v[50:51], 0, v[148:149]
	v_mul_f32_e32 v26, v26, v36
	v_mul_f32_e32 v27, v27, v37
	v_cvt_pk_bf16_f32 v45, v34, v35
	ds_bpermute_b32 v42, v173, v42
	ds_bpermute_b32 v43, v173, v43
	ds_bpermute_b32 v44, v173, v44
	ds_bpermute_b32 v45, v173, v45
	s_waitcnt lgkmcnt(0)
	global_store_dwordx4 v[50:51], v[42:45], off
	v_cvt_pk_bf16_f32 v26, v26, v27
	v_add_f32_e32 v27, 1.0, v30
	v_rcp_f32_e32 v27, v27
	v_add_f32_e32 v30, 1.0, v31
	v_rcp_f32_e32 v30, v30
	v_mul_f32_e32 v28, v28, v32
	v_mul_f32_e32 v27, v28, v27
	v_mul_f32_e32 v28, v29, v33
	v_mul_f32_e32 v29, 0xbfb8aa3b, v22
	v_mul_f32_e32 v28, v28, v30
	v_exp_f32_e32 v29, v29
	v_mul_f32_e32 v30, 0xbfb8aa3b, v23
	v_exp_f32_e32 v30, v30
	v_cvt_pk_bf16_f32 v27, v27, v28
	v_add_f32_e32 v28, 1.0, v29
	v_rcp_f32_e32 v28, v28
	v_add_f32_e32 v29, 1.0, v30
	v_mul_f32_e32 v18, v18, v22
	v_mul_f32_e32 v22, 0xbfb8aa3b, v24
	v_rcp_f32_e32 v29, v29
	v_mul_f32_e32 v19, v19, v23
	v_exp_f32_e32 v22, v22
	v_mul_f32_e32 v23, 0xbfb8aa3b, v25
	v_exp_f32_e32 v23, v23
	v_mul_f32_e32 v18, v18, v28
	v_mul_f32_e32 v19, v19, v29
	v_cvt_pk_bf16_f32 v28, v18, v19
	v_add_f32_e32 v18, 1.0, v22
	v_rcp_f32_e32 v18, v18
	v_add_f32_e32 v19, 1.0, v23
	v_rcp_f32_e32 v19, v19
	v_mul_f32_e32 v20, v20, v24
	v_mul_f32_e32 v18, v20, v18
	v_mul_f32_e32 v20, v21, v25
	v_mul_f32_e32 v19, v20, v19
	v_mul_f32_e32 v20, 0xbfb8aa3b, v14
	v_mul_f32_e32 v21, 0xbfb8aa3b, v15
	v_exp_f32_e32 v20, v20
	v_exp_f32_e32 v21, v21
	v_mul_f32_e32 v10, v10, v14
	v_mul_f32_e32 v14, 0xbfb8aa3b, v16
	v_add_f32_e32 v20, 1.0, v20
	v_add_f32_e32 v21, 1.0, v21
	v_rcp_f32_e32 v20, v20
	v_rcp_f32_e32 v21, v21
	v_mul_f32_e32 v11, v11, v15
	v_exp_f32_e32 v14, v14
	v_mul_f32_e32 v15, 0xbfb8aa3b, v17
	v_add_u32_e32 v34, 0xa0, v156
	v_exp_f32_e32 v15, v15
	v_mad_i64_i32 v[34:35], s[46:47], v34, s60, v[150:151]
	v_lshl_add_u64 v[34:35], v[34:35], 0, v[148:149]
	v_mul_f32_e32 v10, v10, v20
	v_mul_f32_e32 v11, v11, v21
	v_cvt_pk_bf16_f32 v29, v18, v19
	ds_bpermute_b32 v26, v173, v26
	ds_bpermute_b32 v27, v173, v27
	ds_bpermute_b32 v28, v173, v28
	ds_bpermute_b32 v29, v173, v29
	s_waitcnt lgkmcnt(0)
	global_store_dwordx4 v[34:35], v[26:29], off
	v_cvt_pk_bf16_f32 v10, v10, v11
	v_add_f32_e32 v11, 1.0, v14
	v_rcp_f32_e32 v11, v11
	v_add_f32_e32 v14, 1.0, v15
	v_rcp_f32_e32 v14, v14
	v_mul_f32_e32 v12, v12, v16
	v_mul_f32_e32 v11, v12, v11
	v_mul_f32_e32 v12, v13, v17
	v_mul_f32_e32 v13, 0xbfb8aa3b, v6
	v_mul_f32_e32 v12, v12, v14
	v_exp_f32_e32 v13, v13
	v_mul_f32_e32 v14, 0xbfb8aa3b, v7
	v_exp_f32_e32 v14, v14
	v_cvt_pk_bf16_f32 v11, v11, v12
	v_add_f32_e32 v12, 1.0, v13
	v_rcp_f32_e32 v12, v12
	v_add_f32_e32 v13, 1.0, v14
	v_mul_f32_e32 v2, v2, v6
	v_mul_f32_e32 v6, 0xbfb8aa3b, v8
	v_rcp_f32_e32 v13, v13
	v_mul_f32_e32 v3, v3, v7
	v_exp_f32_e32 v6, v6
	v_mul_f32_e32 v7, 0xbfb8aa3b, v9
	v_exp_f32_e32 v7, v7
	v_mul_f32_e32 v2, v2, v12
	v_mul_f32_e32 v3, v3, v13
	v_cvt_pk_bf16_f32 v12, v2, v3
	v_add_f32_e32 v2, 1.0, v6
	v_rcp_f32_e32 v2, v2
	v_add_f32_e32 v3, 1.0, v7
	v_rcp_f32_e32 v3, v3
	v_add_u32_e32 v18, 0xb0, v156
	v_mad_i64_i32 v[18:19], s[46:47], v18, s60, v[150:151]
	v_mul_f32_e32 v4, v4, v8
	v_lshl_add_u64 v[18:19], v[18:19], 0, v[148:149]
	v_mul_f32_e32 v2, v4, v2
	v_mul_f32_e32 v4, v5, v9
	s_andn2_b64 vcc, exec, s[4:5]
	s_mov_b64 s[4:5], -1
	v_mul_f32_e32 v3, v4, v3
	v_cvt_pk_bf16_f32 v13, v2, v3
	ds_bpermute_b32 v10, v173, v10
	ds_bpermute_b32 v11, v173, v11
	ds_bpermute_b32 v12, v173, v12
	ds_bpermute_b32 v13, v173, v13
	s_waitcnt lgkmcnt(0)
	global_store_dwordx4 v[18:19], v[10:13], off
	s_cbranch_vccnz .LBB0_1210
	s_andn2_b64 vcc, exec, s[12:13]
	s_cbranch_vccnz .LBB0_1209
	s_barrier
	s_branch .LBB0_1209
